# baseline (speedup 1.0000x reference)
; DI float h2lo(unsigned u) { return (float)__builtin_bit_cast(f16x2_t, u)[0]; }
; DI float h2hi(unsigned u) { return (float)__builtin_bit_cast(f16x2_t, u)[1]; }
; DI float shfl_xor_l(float v, int mask, int lane) { return __int_as_float(__builtin_amdgcn_ds_bpermute((lane ^ mask) << 2, __float_as_int(v))); }
; DI void ln_phase(const Params& p, const u16* src, const float* g, const float* b, float* dstf, u16* dstb) {
;     ...
;     for (int i = 0; i < 4; ++i) { v[i] = (f32x4){h2lo(raw[i][0]), h2hi(raw[i][0]), h2lo(raw[i][1]), h2hi(raw[i][1])}; s += (v[i][0] + v[i][1]) + (v[i][2] + v[i][3]); }
; #pragma unroll
;     for (int o = 32; o >= 1; o >>= 1) s += shfl_xor_l(s, o, lane);
;     const float mu = s * (1.0f / 1024.0f);
;     float q = 0.f;
; #pragma unroll
;     for (int i = 0; i < 4; ++i) { v[i] = v[i] - mu; q += (v[i][0] * v[i][0] + v[i][1] * v[i][1]) + (v[i][2] * v[i][2] + v[i][3] * v[i][3]); }
; #pragma unroll
;     for (int o = 32; o >= 1; o >>= 1) q += shfl_xor_l(q, o, lane);
.LBB0_1111:
	s_or_b64 exec, exec, s[28:29]
	s_waitcnt vmcnt(3)
	v_cvt_f32_f16_sdwa v60, v52 dst_sel:DWORD dst_unused:UNUSED_PAD src0_sel:WORD_1
	v_cvt_f32_f16_e32 v62, v52
	v_cvt_f32_f16_sdwa v61, v53 dst_sel:DWORD dst_unused:UNUSED_PAD src0_sel:WORD_1
	v_cvt_f32_f16_e32 v63, v53
	s_waitcnt vmcnt(2)
	v_cvt_f32_f16_e32 v66, v50
	v_cvt_f32_f16_e32 v67, v51
	s_waitcnt vmcnt(0)
	v_cvt_f32_f16_sdwa v68, v46 dst_sel:DWORD dst_unused:UNUSED_PAD src0_sel:WORD_1
	v_pk_add_f32 v[60:61], v[62:63], v[60:61]
	v_cvt_f32_f16_sdwa v62, v50 dst_sel:DWORD dst_unused:UNUSED_PAD src0_sel:WORD_1
	v_cvt_f32_f16_sdwa v63, v51 dst_sel:DWORD dst_unused:UNUSED_PAD src0_sel:WORD_1
	v_add_f32_e32 v59, v60, v61
	v_add_f32_e32 v61, 0, v59
	v_cvt_f32_f16_sdwa v59, v48 dst_sel:DWORD dst_unused:UNUSED_PAD src0_sel:WORD_1
	v_pk_add_f32 v[62:63], v[66:67], v[62:63]
	v_cvt_f32_f16_e32 v60, v48
	v_pk_add_f32 v[62:63], v[62:63], v[62:63] op_sel_hi:[0,1]
	v_cvt_f32_f16_sdwa v62, v49 dst_sel:DWORD dst_unused:UNUSED_PAD src0_sel:WORD_1
	v_cvt_f32_f16_e32 v66, v49
	v_add_f32_e32 v67, v60, v59
	v_cvt_f32_f16_sdwa v60, v47 dst_sel:DWORD dst_unused:UNUSED_PAD src0_sel:WORD_1
	s_and_b64 s[2:3], exec, s[38:39]
	v_add_f32_e32 v69, v66, v62
	v_cvt_f32_f16_e32 v66, v46
	v_cvt_f32_f16_e32 v62, v47
	s_or_b64 s[22:23], s[2:3], s[22:23]
	v_pk_add_f32 v[66:67], v[66:67], v[68:69]
	v_pk_add_f32 v[60:61], v[62:63], v[60:61]
	s_nop 0
	v_pk_add_f32 v[60:61], v[66:67], v[60:61]
	s_nop 0
	v_add_f32_e32 v59, v60, v61
	s_nop 1
	v_add_f32_dpp v59, v59, v59 quad_perm:[1,0,3,2] row_mask:0xf bank_mask:0xf
	s_nop 1
	v_add_f32_dpp v59, v59, v59 quad_perm:[2,3,0,1] row_mask:0xf bank_mask:0xf
	s_nop 1
	v_add_f32_dpp v59, v59, v59 row_half_mirror row_mask:0xf bank_mask:0xf
	s_nop 1
	v_add_f32_dpp v59, v59, v59 row_mirror row_mask:0xf bank_mask:0xf
	v_mov_b32_e32 v60, v59
	s_nop 1
	v_permlane16_swap_b32 v60, v59
	v_add_f32_e32 v59, v59, v60
	v_mov_b32_e32 v60, v59
	s_nop 1
	v_permlane32_swap_b32 v60, v59
	v_add_f32_e32 v59, v59, v60
	v_fma_mix_f32 v61, v59, s65, v52 op_sel:[0,0,1] op_sel_hi:[0,0,1]
	v_fma_mix_f32 v60, v59, s65, v52 op_sel_hi:[0,0,1]
	v_fma_mix_f32 v63, v59, s65, v53 op_sel:[0,0,1] op_sel_hi:[0,0,1]
	v_fma_mix_f32 v62, v59, s65, v53 op_sel_hi:[0,0,1]
	v_pk_mul_f32 v[52:53], v[62:63], v[62:63]
	v_pk_mul_f32 v[66:67], v[60:61], v[60:61]
	v_fma_mix_f32 v77, v59, s65, v47 op_sel:[0,0,1] op_sel_hi:[0,0,1]
	v_pk_mov_b32 v[68:69], v[66:67], v[52:53] op_sel:[1,0]
	v_mov_b32_e32 v67, v53
	v_pk_add_f32 v[52:53], v[68:69], v[66:67]
	v_fma_mix_f32 v67, v59, s65, v50 op_sel:[0,0,1] op_sel_hi:[0,0,1]
	v_fma_mix_f32 v66, v59, s65, v50 op_sel_hi:[0,0,1]
	v_fma_mix_f32 v69, v59, s65, v51 op_sel:[0,0,1] op_sel_hi:[0,0,1]
	v_fma_mix_f32 v68, v59, s65, v51 op_sel_hi:[0,0,1]
	v_pk_mul_f32 v[50:51], v[68:69], v[68:69]
	v_pk_mul_f32 v[70:71], v[66:67], v[66:67]
	v_pk_add_f32 v[52:53], v[52:53], v[52:53] op_sel_hi:[0,1]
	v_pk_mov_b32 v[72:73], v[70:71], v[50:51] op_sel:[1,0]
	v_mov_b32_e32 v71, v51
	v_pk_add_f32 v[50:51], v[72:73], v[70:71]
	v_fma_mix_f32 v70, v59, s65, v48 op_sel_hi:[0,0,1]
	v_fma_mix_f32 v71, v59, s65, v48 op_sel:[0,0,1] op_sel_hi:[0,0,1]
	v_mul_f32_e32 v48, v70, v70
	v_fma_mix_f32 v73, v59, s65, v49 op_sel:[0,0,1] op_sel_hi:[0,0,1]
	v_fma_mix_f32 v72, v59, s65, v49 op_sel_hi:[0,0,1]
	v_pk_fma_f32 v[48:49], v[70:71], v[70:71], v[48:49] op_sel_hi:[1,1,0]
	v_pk_add_f32 v[50:51], v[50:51], v[50:51] op_sel_hi:[0,1]
	v_mul_f32_e32 v48, v72, v72
	v_pk_fma_f32 v[74:75], v[72:73], v[72:73], v[48:49] op_sel_hi:[1,1,0]
	v_fma_mix_f32 v76, v59, s65, v47 op_sel_hi:[0,0,1]
	v_fma_mix_f32 v47, v59, s65, v46 op_sel:[0,0,1] op_sel_hi:[0,0,1]
	v_fma_mix_f32 v46, v59, s65, v46 op_sel_hi:[0,0,1]
	v_mul_f32_e32 v48, v46, v46
	v_mul_f32_e32 v74, v47, v47
; DI unsigned pk_bf16(float lo, float hi) { f32x2_t v = {lo, hi}; return __builtin_bit_cast(unsigned, __builtin_convertvector(v, bf16x2_t)); }
; DI float shfl_xor_l(float v, int mask, int lane) { return __int_as_float(__builtin_amdgcn_ds_bpermute((lane ^ mask) << 2, __float_as_int(v))); }
; DI void ln_phase(const Params& p, const u16* src, const float* g, const float* b, float* dstf, u16* dstb) {
;     ...
;     for (int o = 32; o >= 1; o >>= 1) q += shfl_xor_l(q, o, lane);
;     const float rstd = 1.0f / sqrtf(q * (1.0f / 1024.0f) + 1e-5f);
; #pragma unroll
;     for (int i = 0; i < 4; ++i) {
;       const int col = i * 256 + lane * 4;
;       const f32x4 o = v[i] * rstd * gv[i] + bv[i];
;       if (dstf) *(f32x4*)(dstf + (size_t)row * D + col) = o;
;       if (dstb) { u32x2 ob; ob[0] = pk_bf16(o[0], o[1]); ob[1] = pk_bf16(o[2], o[3]); *(u32x2*)(dstb + (size_t)row * D + col) = ob; }
;     }
; #pragma unroll
;     for (int i = 0; i < 4; ++i) raw[i] = nxt[i];
;   }
	v_mul_f32_e32 v52, v76, v76
	v_mul_f32_e32 v50, v77, v77
	v_pk_add_f32 v[48:49], v[48:49], v[74:75]
	v_pk_add_f32 v[50:51], v[52:53], v[50:51]
	s_nop 0
	v_pk_add_f32 v[48:49], v[48:49], v[50:51]
	s_nop 0
	v_add_f32_e32 v48, v48, v49
	s_nop 1
	v_add_f32_dpp v48, v48, v48 quad_perm:[1,0,3,2] row_mask:0xf bank_mask:0xf
	s_nop 1
	v_add_f32_dpp v48, v48, v48 quad_perm:[2,3,0,1] row_mask:0xf bank_mask:0xf
	s_nop 1
	v_add_f32_dpp v48, v48, v48 row_half_mirror row_mask:0xf bank_mask:0xf
	s_nop 1
	v_add_f32_dpp v48, v48, v48 row_mirror row_mask:0xf bank_mask:0xf
	v_mov_b32_e32 v49, v48
	s_nop 1
	v_permlane16_swap_b32 v49, v48
	v_add_f32_e32 v48, v48, v49
	v_mov_b32_e32 v49, v48
	s_nop 1
	v_permlane32_swap_b32 v49, v48
	v_add_f32_e32 v48, v48, v49
	v_mov_b32_e32 v49, 0x3727c5ac
	v_fmamk_f32 v48, v48, 0x3a800000, v49
	v_cmp_gt_f32_e32 vcc, s66, v48
	v_mul_f32_e32 v49, 0x4f800000, v48
	s_nop 0
	v_cndmask_b32_e32 v48, v48, v49, vcc
	v_sqrt_f32_e32 v49, v48
	s_nop 0
	v_add_u32_e32 v50, -1, v49
	v_fma_f32 v51, -v50, v49, v48
	v_cmp_ge_f32_e64 s[38:39], 0, v51
	v_add_u32_e32 v51, 1, v49
	s_nop 0
	v_cndmask_b32_e64 v50, v49, v50, s[38:39]
	v_fma_f32 v49, -v51, v49, v48
	v_cmp_lt_f32_e64 s[38:39], 0, v49
	s_nop 1
	v_cndmask_b32_e64 v49, v50, v51, s[38:39]
	v_mul_f32_e32 v50, 0x37800000, v49
	v_cndmask_b32_e32 v49, v49, v50, vcc
	v_mov_b32_e32 v50, 0x260
	v_cmp_class_f32_e32 vcc, v48, v50
	s_nop 1
	v_cndmask_b32_e32 v48, v49, v48, vcc
	v_div_scale_f32 v49, s[2:3], v48, v48, 1.0
	v_rcp_f32_e32 v50, v49
	s_mov_b32 s2, 0xaa80000
	v_fma_f32 v51, -v49, v50, 1.0
	v_fmac_f32_e32 v50, v51, v50
	v_div_scale_f32 v51, vcc, 1.0, v48, 1.0
	v_mul_f32_e32 v52, v51, v50
	v_fma_f32 v53, -v49, v52, v51
	v_fmac_f32_e32 v52, v53, v50
	v_fma_f32 v49, -v49, v52, v51
	v_div_fmas_f32 v49, v49, v50, v52
	v_div_fixup_f32 v48, v49, v48, 1.0
	v_pk_mul_f32 v[50:51], v[60:61], v[48:49] op_sel_hi:[1,0]
	v_pk_mul_f32 v[52:53], v[62:63], v[48:49] op_sel_hi:[1,0]
	v_pk_fma_f32 v[50:51], v[0:1], v[50:51], v[8:9]
	v_pk_fma_f32 v[52:53], v[2:3], v[52:53], v[10:11]
	v_cvt_pk_bf16_f32 v50, v50, v51
	v_cvt_pk_bf16_f32 v51, v52, v53
	v_lshl_add_u64 v[52:53], v[34:35], 0, v[64:65]
	v_add_co_u32_e32 v52, vcc, s2, v52
	v_pk_mul_f32 v[60:61], v[68:69], v[48:49] op_sel_hi:[1,0]
	s_nop 0
	v_addc_co_u32_e32 v53, vcc, 0, v53, vcc
	global_store_dwordx2 v[52:53], v[50:51], off
	v_pk_mul_f32 v[50:51], v[66:67], v[48:49] op_sel_hi:[1,0]
	v_pk_fma_f32 v[60:61], v[6:7], v[60:61], v[14:15]
	v_pk_fma_f32 v[50:51], v[4:5], v[50:51], v[12:13]
	v_pk_mul_f32 v[46:47], v[46:47], v[48:49] op_sel_hi:[1,0]
	v_cvt_pk_bf16_f32 v50, v50, v51
	v_cvt_pk_bf16_f32 v51, v60, v61
	global_store_dwordx2 v[52:53], v[50:51], off offset:512
	v_pk_mul_f32 v[50:51], v[70:71], v[48:49] op_sel_hi:[1,0]
	v_pk_mul_f32 v[60:61], v[72:73], v[48:49] op_sel_hi:[1,0]
	v_pk_mul_f32 v[48:49], v[76:77], v[48:49] op_sel_hi:[1,0]
	v_pk_fma_f32 v[60:61], v[18:19], v[60:61], v[26:27]
	v_pk_fma_f32 v[50:51], v[16:17], v[50:51], v[24:25]
	v_pk_fma_f32 v[48:49], v[22:23], v[48:49], v[30:31]
	v_pk_fma_f32 v[46:47], v[20:21], v[46:47], v[28:29]
	v_readlane_b32 s2, v255, 14
	v_cvt_pk_bf16_f32 v50, v50, v51
	v_cvt_pk_bf16_f32 v51, v60, v61
	v_cvt_pk_bf16_f32 v46, v46, v47
	v_cvt_pk_bf16_f32 v47, v48, v49
	v_readlane_b32 s3, v255, 15
	global_store_dwordx2 v[52:53], v[50:51], off offset:1024
	global_store_dwordx2 v[52:53], v[46:47], off offset:1536
	v_lshl_add_u64 v[34:35], v[34:35], 0, s[2:3]
	v_lshl_add_u64 v[36:37], v[36:37], 0, s[2:3]
	v_mov_b32_e32 v52, v38
	v_mov_b32_e32 v53, v39
	v_mov_b32_e32 v50, v40
	v_mov_b32_e32 v51, v41
	v_mov_b32_e32 v48, v42
	v_mov_b32_e32 v49, v43
	v_mov_b32_e32 v46, v44
	v_mov_b32_e32 v47, v45
	s_andn2_b64 exec, exec, s[22:23]
	s_cbranch_execz .LBB0_1114

; DI float h2lo(unsigned u) { return (float)__builtin_bit_cast(f16x2_t, u)[0]; }
; DI float h2hi(unsigned u) { return (float)__builtin_bit_cast(f16x2_t, u)[1]; }
; DI float shfl_xor_l(float v, int mask, int lane) { return __int_as_float(__builtin_amdgcn_ds_bpermute((lane ^ mask) << 2, __float_as_int(v))); }
; DI void ln_phase(const Params& p, const u16* src, const float* g, const float* b, float* dstf, u16* dstb) {
;     ...
;     for (int i = 0; i < 4; ++i) { v[i] = (f32x4){h2lo(raw[i][0]), h2hi(raw[i][0]), h2lo(raw[i][1]), h2hi(raw[i][1])}; s += (v[i][0] + v[i][1]) + (v[i][2] + v[i][3]); }
; #pragma unroll
;     for (int o = 32; o >= 1; o >>= 1) s += shfl_xor_l(s, o, lane);
;     const float mu = s * (1.0f / 1024.0f);
;     float q = 0.f;
; #pragma unroll
;     for (int i = 0; i < 4; ++i) { v[i] = v[i] - mu; q += (v[i][0] * v[i][0] + v[i][1] * v[i][1]) + (v[i][2] * v[i][2] + v[i][3] * v[i][3]); }
; #pragma unroll
;     for (int o = 32; o >= 1; o >>= 1) q += shfl_xor_l(q, o, lane);
;     const float rstd = 1.0f / sqrtf(q * (1.0f / 1024.0f) + 1e-5f);
; #pragma unroll
;     for (int i = 0; i < 4; ++i) {
;       const int col = i * 256 + lane * 4;
;       const f32x4 o = v[i] * rstd * gv[i] + bv[i];
;       if (dstf) *(f32x4*)(dstf + (size_t)row * D + col) = o;
.LBB0_1327:
	s_or_b64 exec, exec, s[38:39]
	s_waitcnt vmcnt(3)
	v_cvt_f32_f16_sdwa v56, v54 dst_sel:DWORD dst_unused:UNUSED_PAD src0_sel:WORD_1
	v_cvt_f32_f16_e32 v58, v54
	v_cvt_f32_f16_sdwa v57, v55 dst_sel:DWORD dst_unused:UNUSED_PAD src0_sel:WORD_1
	v_cvt_f32_f16_e32 v59, v55
	s_waitcnt vmcnt(2)
	v_cvt_f32_f16_sdwa v60, v52 dst_sel:DWORD dst_unused:UNUSED_PAD src0_sel:WORD_1
	v_cvt_f32_f16_e32 v62, v52
	v_cvt_f32_f16_sdwa v61, v53 dst_sel:DWORD dst_unused:UNUSED_PAD src0_sel:WORD_1
	v_cvt_f32_f16_e32 v63, v53
	v_pk_add_f32 v[56:57], v[58:59], v[56:57]
	s_waitcnt vmcnt(1)
	v_cvt_f32_f16_sdwa v66, v35 dst_sel:DWORD dst_unused:UNUSED_PAD src0_sel:WORD_1
	v_add_f32_e32 v37, v56, v57
	v_pk_add_f32 v[58:59], v[62:63], v[60:61]
	v_add_f32_e32 v57, 0, v37
	v_pk_add_f32 v[58:59], v[58:59], v[58:59] op_sel_hi:[0,1]
	v_cvt_f32_f16_sdwa v37, v34 dst_sel:DWORD dst_unused:UNUSED_PAD src0_sel:WORD_1
	v_cvt_f32_f16_e32 v61, v34
	v_cvt_f32_f16_e32 v67, v35
	s_waitcnt vmcnt(0)
	v_cvt_f32_f16_sdwa v60, v32 dst_sel:DWORD dst_unused:UNUSED_PAD src0_sel:WORD_1
	v_cvt_f32_f16_e32 v62, v32
	v_cvt_f32_f16_sdwa v56, v33 dst_sel:DWORD dst_unused:UNUSED_PAD src0_sel:WORD_1
	v_cvt_f32_f16_e32 v58, v33
	v_add_f32_e32 v63, v61, v37
	v_add_f32_e32 v61, v67, v66
	v_pk_add_f32 v[60:61], v[62:63], v[60:61]
	v_pk_add_f32 v[56:57], v[58:59], v[56:57]
	s_nop 0
	v_pk_add_f32 v[56:57], v[60:61], v[56:57]
	s_nop 0
	v_add_f32_e32 v37, v56, v57
	s_nop 1
	v_add_f32_dpp v37, v37, v37 quad_perm:[1,0,3,2] row_mask:0xf bank_mask:0xf
	s_nop 1
	v_add_f32_dpp v37, v37, v37 quad_perm:[2,3,0,1] row_mask:0xf bank_mask:0xf
	s_nop 1
	v_add_f32_dpp v37, v37, v37 row_half_mirror row_mask:0xf bank_mask:0xf
	s_nop 1
	v_add_f32_dpp v37, v37, v37 row_mirror row_mask:0xf bank_mask:0xf
	v_mov_b32_e32 v56, v37
	s_nop 1
	v_permlane16_swap_b32 v56, v37
	v_add_f32_e32 v37, v37, v56
	v_mov_b32_e32 v56, v37
	s_nop 1
	v_permlane32_swap_b32 v56, v37
	v_add_f32_e32 v37, v37, v56
	v_fma_mix_f32 v67, v37, s65, v54 op_sel:[0,0,1] op_sel_hi:[0,0,1]
	v_fma_mix_f32 v66, v37, s65, v54 op_sel_hi:[0,0,1]
	v_fma_mix_f32 v77, v37, s65, v55 op_sel:[0,0,1] op_sel_hi:[0,0,1]
	v_fma_mix_f32 v76, v37, s65, v55 op_sel_hi:[0,0,1]
	v_fma_mix_f32 v61, v37, s65, v53 op_sel:[0,0,1] op_sel_hi:[0,0,1]
	v_fma_mix_f32 v60, v37, s65, v53 op_sel_hi:[0,0,1]
	v_fma_mix_f32 v63, v37, s65, v52 op_sel:[0,0,1] op_sel_hi:[0,0,1]
	v_fma_mix_f32 v62, v37, s65, v52 op_sel_hi:[0,0,1]
	v_pk_mul_f32 v[52:53], v[76:77], v[76:77]
	v_pk_mul_f32 v[54:55], v[66:67], v[66:67]
	v_pk_mul_f32 v[56:57], v[60:61], v[60:61]
	v_pk_mov_b32 v[58:59], v[54:55], v[52:53] op_sel:[1,0]
	v_mov_b32_e32 v55, v53
	v_pk_add_f32 v[52:53], v[58:59], v[54:55]
	v_fma_mix_f32 v58, v37, s65, v34 op_sel_hi:[0,0,1]
	v_pk_add_f32 v[68:69], v[52:53], v[52:53] op_sel_hi:[0,1]
	v_pk_mul_f32 v[52:53], v[62:63], v[62:63]
	v_fma_mix_f32 v59, v37, s65, v34 op_sel:[0,0,1] op_sel_hi:[0,0,1]
	v_mul_f32_e32 v34, v58, v58
	v_pk_mov_b32 v[54:55], v[52:53], v[56:57] op_sel:[1,0]
	v_mov_b32_e32 v53, v57
	v_fma_mix_f32 v57, v37, s65, v35 op_sel:[0,0,1] op_sel_hi:[0,0,1]
	v_fma_mix_f32 v56, v37, s65, v35 op_sel_hi:[0,0,1]
	v_pk_fma_f32 v[34:35], v[58:59], v[58:59], v[34:35] op_sel_hi:[1,1,0]
	v_pk_add_f32 v[52:53], v[54:55], v[52:53]
	v_mul_f32_e32 v34, v56, v56
	v_pk_add_f32 v[78:79], v[52:53], v[52:53] op_sel_hi:[0,1]
	v_pk_fma_f32 v[80:81], v[56:57], v[56:57], v[34:35] op_sel_hi:[1,1,0]
	v_fma_mix_f32 v53, v37, s65, v33 op_sel:[0,0,1] op_sel_hi:[0,0,1]
	v_fma_mix_f32 v52, v37, s65, v33 op_sel_hi:[0,0,1]
	v_fma_mix_f32 v55, v37, s65, v32 op_sel:[0,0,1] op_sel_hi:[0,0,1]
	v_fma_mix_f32 v54, v37, s65, v32 op_sel_hi:[0,0,1]
	v_mul_f32_e32 v34, v54, v54
	v_mul_f32_e32 v80, v55, v55
	v_mul_f32_e32 v68, v52, v52
	v_mul_f32_e32 v78, v53, v53
	v_pk_add_f32 v[32:33], v[34:35], v[80:81]
	v_pk_add_f32 v[34:35], v[68:69], v[78:79]
	s_nop 0
	v_pk_add_f32 v[32:33], v[32:33], v[34:35]
	s_nop 0
	v_add_f32_e32 v32, v32, v33
	s_nop 1
	v_add_f32_dpp v32, v32, v32 quad_perm:[1,0,3,2] row_mask:0xf bank_mask:0xf
	s_nop 1
	v_add_f32_dpp v32, v32, v32 quad_perm:[2,3,0,1] row_mask:0xf bank_mask:0xf
	s_nop 1
	v_add_f32_dpp v32, v32, v32 row_half_mirror row_mask:0xf bank_mask:0xf
	s_nop 1
	v_add_f32_dpp v32, v32, v32 row_mirror row_mask:0xf bank_mask:0xf
	v_mov_b32_e32 v33, v32
	s_nop 1
	v_permlane16_swap_b32 v33, v32
	v_add_f32_e32 v32, v32, v33
	v_mov_b32_e32 v33, v32
	s_nop 1
	v_permlane32_swap_b32 v33, v32
	v_add_f32_e32 v32, v32, v33
	v_mov_b32_e32 v33, 0x3727c5ac
	v_fmamk_f32 v32, v32, 0x3a800000, v33
	v_mul_f32_e32 v33, 0x4f800000, v32
	v_cmp_gt_f32_e32 vcc, s66, v32
	s_nop 1
	v_cndmask_b32_e32 v32, v32, v33, vcc
	v_sqrt_f32_e32 v33, v32
	s_nop 0
	v_add_u32_e32 v34, -1, v33
	v_add_u32_e32 v35, 1, v33
	v_fma_f32 v37, -v34, v33, v32
	v_fma_f32 v68, -v35, v33, v32
	v_cmp_ge_f32_e64 s[38:39], 0, v37
	s_nop 1
	v_cndmask_b32_e64 v33, v33, v34, s[38:39]
	v_cmp_lt_f32_e64 s[38:39], 0, v68
	s_nop 1
	v_cndmask_b32_e64 v33, v33, v35, s[38:39]
	v_mul_f32_e32 v34, 0x37800000, v33
	v_cndmask_b32_e32 v33, v33, v34, vcc
	v_mov_b32_e32 v34, 0x260
	v_cmp_class_f32_e32 vcc, v32, v34
	s_nop 1
	v_cndmask_b32_e32 v32, v33, v32, vcc
	v_div_scale_f32 v33, s[2:3], v32, v32, 1.0
	v_rcp_f32_e32 v34, v33
	v_div_scale_f32 v35, vcc, 1.0, v32, 1.0
	v_fma_f32 v37, -v33, v34, 1.0
	v_fmac_f32_e32 v34, v37, v34
	v_mul_f32_e32 v37, v35, v34
	v_fma_f32 v68, -v33, v37, v35
	v_fmac_f32_e32 v37, v68, v34
	v_fma_f32 v33, -v33, v37, v35
	v_div_fmas_f32 v33, v33, v34, v37
	v_div_fixup_f32 v68, v33, v32, 1.0
	v_pk_mul_f32 v[32:33], v[66:67], v[68:69] op_sel_hi:[1,0]
	v_pk_mul_f32 v[34:35], v[76:77], v[68:69] op_sel_hi:[1,0]
	v_cndmask_b32_e64 v37, 0, 1, s[28:29]
	v_pk_fma_f32 v[34:35], v[2:3], v[34:35], v[10:11]
	v_cmp_ne_u32_e64 s[38:39], 1, v37
	s_andn2_b64 vcc, exec, s[28:29]
	v_pk_fma_f32 v[32:33], v[0:1], v[32:33], v[8:9]
	s_cbranch_vccnz .LBB0_1329
	global_store_dwordx4 v[42:43], v[32:35], off offset:-2048
